# v34 with the GEMM K-loop's 20 already-satisfied lgkmcnt waits and 4 back-to-back setprio pairs removed
# baseline (speedup 1.0000x reference)
.LBB0_270:
	v_add_u32_e32 v140, 0x10000, v223
	v_add_u32_e32 v156, 0x14000, v223
	s_waitcnt lgkmcnt(0)
	ds_read_b128 v[128:131], v140
	ds_read_b128 v[132:135], v140 offset:1024
	ds_read_b128 v[136:139], v140 offset:2048
	ds_read_b128 v[140:143], v140 offset:3072
	ds_read_b128 v[144:147], v156
	ds_read_b128 v[148:151], v156 offset:1024
	ds_read_b128 v[152:155], v156 offset:2048
	ds_read_b128 v[182:185], v156 offset:3072
	s_add_i32 s44, s3, 0x80
	s_cmp_eq_u32 s100, s43
	s_cselect_b32 s45, s25, s44
	s_cselect_b32 s90, s2, s42
	s_add_i32 s44, s45, 0x80
	s_add_i32 s48, s73, s3
	s_mov_b32 s76, s46
	s_mov_b32 m0, s96
	ds_read_b128 v[186:189], v224
	ds_read_b128 v[190:193], v224 offset:1024
	ds_read_b128 v[232:235], v224 offset:2048
	ds_read_b128 v[236:239], v224 offset:3072
	ds_read_b128 v[240:243], v224 offset:4096
	ds_read_b128 v[244:247], v224 offset:5120
	ds_read_b128 v[248:251], v224 offset:6144
	ds_read_b128 v[202:205], v224 offset:7168
	buffer_load_dwordx4 v217, s[76:79], s48 offen lds
	s_mov_b32 m0, s97
	s_nop 0
	buffer_load_dwordx4 v219, s[76:79], s48 offen lds
	s_waitcnt vmcnt(8)
	s_waitcnt lgkmcnt(0)
	s_barrier
	s_setprio 1
	v_mfma_f32_16x16x32_bf16 v[124:127], v[128:131], v[186:189], v[124:127]
	v_mfma_f32_16x16x32_bf16 v[120:123], v[136:139], v[186:189], v[120:123]
	v_mfma_f32_16x16x32_bf16 v[108:111], v[128:131], v[232:235], v[108:111]
	v_mfma_f32_16x16x32_bf16 v[104:107], v[136:139], v[232:235], v[104:107]
	v_mfma_f32_16x16x32_bf16 v[92:95], v[128:131], v[240:243], v[92:95]
	v_mfma_f32_16x16x32_bf16 v[88:91], v[136:139], v[240:243], v[88:91]
	v_mfma_f32_16x16x32_bf16 v[76:79], v[128:131], v[248:251], v[76:79]
	v_mfma_f32_16x16x32_bf16 v[72:75], v[136:139], v[248:251], v[72:75]
	v_mfma_f32_16x16x32_bf16 v[124:127], v[132:135], v[190:193], v[124:127]
	v_mfma_f32_16x16x32_bf16 v[120:123], v[140:143], v[190:193], v[120:123]
	v_mfma_f32_16x16x32_bf16 v[108:111], v[132:135], v[236:239], v[108:111]
	v_mfma_f32_16x16x32_bf16 v[104:107], v[140:143], v[236:239], v[104:107]
	v_mfma_f32_16x16x32_bf16 v[92:95], v[132:135], v[244:247], v[92:95]
	v_mfma_f32_16x16x32_bf16 v[88:91], v[140:143], v[244:247], v[88:91]
	v_mfma_f32_16x16x32_bf16 v[76:79], v[132:135], v[202:205], v[76:79]
	v_mfma_f32_16x16x32_bf16 v[72:75], v[140:143], v[202:205], v[72:75]
	v_mfma_f32_16x16x32_bf16 v[116:119], v[144:147], v[186:189], v[116:119]
	v_mfma_f32_16x16x32_bf16 v[112:115], v[152:155], v[186:189], v[112:115]
	v_mfma_f32_16x16x32_bf16 v[100:103], v[144:147], v[232:235], v[100:103]
	v_mfma_f32_16x16x32_bf16 v[96:99], v[152:155], v[232:235], v[96:99]
	v_mfma_f32_16x16x32_bf16 v[84:87], v[144:147], v[240:243], v[84:87]
	v_mfma_f32_16x16x32_bf16 v[80:83], v[152:155], v[240:243], v[80:83]
	v_mfma_f32_16x16x32_bf16 v[68:71], v[144:147], v[248:251], v[68:71]
	v_mfma_f32_16x16x32_bf16 v[64:67], v[152:155], v[248:251], v[64:67]
	v_mfma_f32_16x16x32_bf16 v[116:119], v[148:151], v[190:193], v[116:119]
	v_mfma_f32_16x16x32_bf16 v[112:115], v[182:185], v[190:193], v[112:115]
	v_mfma_f32_16x16x32_bf16 v[100:103], v[148:151], v[236:239], v[100:103]
	v_mfma_f32_16x16x32_bf16 v[96:99], v[182:185], v[236:239], v[96:99]
	v_mfma_f32_16x16x32_bf16 v[84:87], v[148:151], v[244:247], v[84:87]
	v_mfma_f32_16x16x32_bf16 v[80:83], v[182:185], v[244:247], v[80:83]
	v_mfma_f32_16x16x32_bf16 v[68:71], v[148:151], v[202:205], v[68:71]
	v_mfma_f32_16x16x32_bf16 v[64:67], v[182:185], v[202:205], v[64:67]
	s_setprio 0
	s_barrier
	s_mov_b32 m0, s71
	s_mov_b32 s48, s94
	s_mov_b32 s50, s78
	s_mov_b32 s51, s79
	ds_read_b128 v[186:189], v224 offset:16384
	ds_read_b128 v[190:193], v224 offset:17408
	ds_read_b128 v[202:205], v224 offset:18432
	ds_read_b128 v[232:235], v224 offset:19456
	ds_read_b128 v[236:239], v224 offset:20480
	ds_read_b128 v[240:243], v224 offset:21504
	ds_read_b128 v[244:247], v224 offset:22528
	ds_read_b128 v[248:251], v224 offset:23552
	buffer_load_dwordx4 v218, s[48:51], s90 offen lds
	s_mov_b32 m0, s28
	s_add_i32 s91, s90, s64
	buffer_load_dwordx4 v220, s[48:51], s90 offen lds
	s_mov_b32 m0, s29
	s_nop 0
	buffer_load_dwordx4 v218, s[48:51], s91 offen lds
	s_mov_b32 m0, s26
	s_nop 0
	buffer_load_dwordx4 v220, s[48:51], s91 offen lds
	s_mov_b32 m0, s70
	s_nop 0
	buffer_load_dwordx4 v217, s[76:79], s45 offen lds
	s_mov_b32 m0, s27
	s_nop 0
	buffer_load_dwordx4 v219, s[76:79], s45 offen lds
	s_waitcnt vmcnt(8)
	s_waitcnt lgkmcnt(0)
	s_barrier
	s_setprio 1
	v_mfma_f32_16x16x32_bf16 v[60:63], v[128:131], v[186:189], v[60:63]
	v_mfma_f32_16x16x32_bf16 v[56:59], v[136:139], v[186:189], v[56:59]
	v_mfma_f32_16x16x32_bf16 v[44:47], v[128:131], v[202:205], v[44:47]
	v_mfma_f32_16x16x32_bf16 v[40:43], v[136:139], v[202:205], v[40:43]
	v_mfma_f32_16x16x32_bf16 v[28:31], v[128:131], v[236:239], v[28:31]
	v_mfma_f32_16x16x32_bf16 v[24:27], v[136:139], v[236:239], v[24:27]
	v_mfma_f32_16x16x32_bf16 v[12:15], v[128:131], v[244:247], v[12:15]
	v_mfma_f32_16x16x32_bf16 v[8:11], v[136:139], v[244:247], v[8:11]
	v_mfma_f32_16x16x32_bf16 v[60:63], v[132:135], v[190:193], v[60:63]
	v_mfma_f32_16x16x32_bf16 v[56:59], v[140:143], v[190:193], v[56:59]
	v_mfma_f32_16x16x32_bf16 v[44:47], v[132:135], v[232:235], v[44:47]
	v_mfma_f32_16x16x32_bf16 v[40:43], v[140:143], v[232:235], v[40:43]
	v_mfma_f32_16x16x32_bf16 v[28:31], v[132:135], v[240:243], v[28:31]
	v_mfma_f32_16x16x32_bf16 v[24:27], v[140:143], v[240:243], v[24:27]
	v_mfma_f32_16x16x32_bf16 v[12:15], v[132:135], v[248:251], v[12:15]
	v_mfma_f32_16x16x32_bf16 v[8:11], v[140:143], v[248:251], v[8:11]
	v_mfma_f32_16x16x32_bf16 v[52:55], v[144:147], v[186:189], v[52:55]
	v_mfma_f32_16x16x32_bf16 v[48:51], v[152:155], v[186:189], v[48:51]
	v_mfma_f32_16x16x32_bf16 v[36:39], v[144:147], v[202:205], v[36:39]
	v_mfma_f32_16x16x32_bf16 v[32:35], v[152:155], v[202:205], v[32:35]
	v_mfma_f32_16x16x32_bf16 v[20:23], v[144:147], v[236:239], v[20:23]
	v_mfma_f32_16x16x32_bf16 v[16:19], v[152:155], v[236:239], v[16:19]
	v_mfma_f32_16x16x32_bf16 v[4:7], v[144:147], v[244:247], v[4:7]
	v_mfma_f32_16x16x32_bf16 v[0:3], v[152:155], v[244:247], v[0:3]
	v_mfma_f32_16x16x32_bf16 v[52:55], v[148:151], v[190:193], v[52:55]
	v_mfma_f32_16x16x32_bf16 v[48:51], v[182:185], v[190:193], v[48:51]
	v_mfma_f32_16x16x32_bf16 v[36:39], v[148:151], v[232:235], v[36:39]
	v_mfma_f32_16x16x32_bf16 v[32:35], v[182:185], v[232:235], v[32:35]
	v_mfma_f32_16x16x32_bf16 v[20:23], v[148:151], v[240:243], v[20:23]
	v_mfma_f32_16x16x32_bf16 v[16:19], v[182:185], v[240:243], v[16:19]
	v_mfma_f32_16x16x32_bf16 v[4:7], v[148:151], v[248:251], v[4:7]
	v_mfma_f32_16x16x32_bf16 v[0:3], v[182:185], v[248:251], v[0:3]
	s_setprio 0
	s_barrier
	v_add_u32_e32 v140, 0x18000, v223
	v_add_u32_e32 v156, 0x1c000, v223
	ds_read_b128 v[128:131], v140
	ds_read_b128 v[132:135], v140 offset:1024
	ds_read_b128 v[136:139], v140 offset:2048
	ds_read_b128 v[140:143], v140 offset:3072
	ds_read_b128 v[144:147], v156
	ds_read_b128 v[148:151], v156 offset:1024
	ds_read_b128 v[152:155], v156 offset:2048
	ds_read_b128 v[182:185], v156 offset:3072
	s_add_i32 s45, s45, s73
	s_mov_b32 m0, s62
	ds_read_b128 v[186:189], v224 offset:32768
	ds_read_b128 v[190:193], v224 offset:33792
	ds_read_b128 v[202:205], v224 offset:34816
	ds_read_b128 v[232:235], v224 offset:35840
	ds_read_b128 v[236:239], v224 offset:36864
	ds_read_b128 v[240:243], v224 offset:37888
	ds_read_b128 v[244:247], v224 offset:38912
	ds_read_b128 v[248:251], v224 offset:39936
	buffer_load_dwordx4 v217, s[76:79], s45 offen lds
	s_mov_b32 m0, s63
	s_nop 0
	buffer_load_dwordx4 v219, s[76:79], s45 offen lds
	s_waitcnt vmcnt(8)
	s_waitcnt lgkmcnt(0)
	s_barrier
	s_setprio 1
	v_mfma_f32_16x16x32_bf16 v[124:127], v[128:131], v[186:189], v[124:127]
	v_mfma_f32_16x16x32_bf16 v[120:123], v[136:139], v[186:189], v[120:123]
	v_mfma_f32_16x16x32_bf16 v[108:111], v[128:131], v[202:205], v[108:111]
	v_mfma_f32_16x16x32_bf16 v[104:107], v[136:139], v[202:205], v[104:107]
	v_mfma_f32_16x16x32_bf16 v[92:95], v[128:131], v[236:239], v[92:95]
	v_mfma_f32_16x16x32_bf16 v[88:91], v[136:139], v[236:239], v[88:91]
	v_mfma_f32_16x16x32_bf16 v[76:79], v[128:131], v[244:247], v[76:79]
	v_mfma_f32_16x16x32_bf16 v[72:75], v[136:139], v[244:247], v[72:75]
	v_mfma_f32_16x16x32_bf16 v[124:127], v[132:135], v[190:193], v[124:127]
	v_mfma_f32_16x16x32_bf16 v[120:123], v[140:143], v[190:193], v[120:123]
	v_mfma_f32_16x16x32_bf16 v[108:111], v[132:135], v[232:235], v[108:111]
	v_mfma_f32_16x16x32_bf16 v[104:107], v[140:143], v[232:235], v[104:107]
	v_mfma_f32_16x16x32_bf16 v[92:95], v[132:135], v[240:243], v[92:95]
	v_mfma_f32_16x16x32_bf16 v[88:91], v[140:143], v[240:243], v[88:91]
	v_mfma_f32_16x16x32_bf16 v[76:79], v[132:135], v[248:251], v[76:79]
	v_mfma_f32_16x16x32_bf16 v[72:75], v[140:143], v[248:251], v[72:75]
	v_mfma_f32_16x16x32_bf16 v[116:119], v[144:147], v[186:189], v[116:119]
	v_mfma_f32_16x16x32_bf16 v[112:115], v[152:155], v[186:189], v[112:115]
	v_mfma_f32_16x16x32_bf16 v[100:103], v[144:147], v[202:205], v[100:103]
	v_mfma_f32_16x16x32_bf16 v[96:99], v[152:155], v[202:205], v[96:99]
	v_mfma_f32_16x16x32_bf16 v[84:87], v[144:147], v[236:239], v[84:87]
	v_mfma_f32_16x16x32_bf16 v[80:83], v[152:155], v[236:239], v[80:83]
	v_mfma_f32_16x16x32_bf16 v[68:71], v[144:147], v[244:247], v[68:71]
	v_mfma_f32_16x16x32_bf16 v[64:67], v[152:155], v[244:247], v[64:67]
	v_mfma_f32_16x16x32_bf16 v[116:119], v[148:151], v[190:193], v[116:119]
	v_mfma_f32_16x16x32_bf16 v[112:115], v[182:185], v[190:193], v[112:115]
	v_mfma_f32_16x16x32_bf16 v[100:103], v[148:151], v[232:235], v[100:103]
	v_mfma_f32_16x16x32_bf16 v[96:99], v[182:185], v[232:235], v[96:99]
	v_mfma_f32_16x16x32_bf16 v[84:87], v[148:151], v[240:243], v[84:87]
	v_mfma_f32_16x16x32_bf16 v[80:83], v[182:185], v[240:243], v[80:83]
	v_mfma_f32_16x16x32_bf16 v[68:71], v[148:151], v[248:251], v[68:71]
	v_mfma_f32_16x16x32_bf16 v[64:67], v[182:185], v[248:251], v[64:67]
	s_setprio 0
	s_barrier
	s_mov_b32 m0, s88
	s_add_i32 s45, s90, 0x80
	ds_read_b128 v[186:189], v224 offset:49152
	ds_read_b128 v[190:193], v224 offset:50176
	ds_read_b128 v[202:205], v224 offset:51200
	ds_read_b128 v[232:235], v224 offset:52224
	ds_read_b128 v[236:239], v224 offset:53248
	ds_read_b128 v[240:243], v224 offset:54272
	ds_read_b128 v[244:247], v224 offset:55296
	ds_read_b128 v[248:251], v224 offset:56320
	buffer_load_dwordx4 v218, s[48:51], s45 offen lds
	s_mov_b32 m0, s82
	s_nop 0
	buffer_load_dwordx4 v220, s[48:51], s45 offen lds
	s_add_i32 s45, s45, s64
	s_mov_b32 m0, s58
	s_nop 0
	buffer_load_dwordx4 v218, s[48:51], s45 offen lds
	s_mov_b32 m0, s59
	s_nop 0
	buffer_load_dwordx4 v220, s[48:51], s45 offen lds
	s_mov_b32 m0, s83
	s_nop 0
	buffer_load_dwordx4 v217, s[76:79], s44 offen lds
	s_mov_b32 m0, s89
	s_nop 0
	buffer_load_dwordx4 v219, s[76:79], s44 offen lds
	s_waitcnt vmcnt(8)
	s_waitcnt lgkmcnt(0)
	s_barrier
	s_setprio 1
	v_mfma_f32_16x16x32_bf16 v[60:63], v[128:131], v[186:189], v[60:63]
	v_mfma_f32_16x16x32_bf16 v[56:59], v[136:139], v[186:189], v[56:59]
	v_mfma_f32_16x16x32_bf16 v[44:47], v[128:131], v[202:205], v[44:47]
	v_mfma_f32_16x16x32_bf16 v[40:43], v[136:139], v[202:205], v[40:43]
	v_mfma_f32_16x16x32_bf16 v[28:31], v[128:131], v[236:239], v[28:31]
	v_mfma_f32_16x16x32_bf16 v[24:27], v[136:139], v[236:239], v[24:27]
	v_mfma_f32_16x16x32_bf16 v[12:15], v[128:131], v[244:247], v[12:15]
	v_mfma_f32_16x16x32_bf16 v[8:11], v[136:139], v[244:247], v[8:11]
	v_mfma_f32_16x16x32_bf16 v[60:63], v[132:135], v[190:193], v[60:63]
	v_mfma_f32_16x16x32_bf16 v[56:59], v[140:143], v[190:193], v[56:59]
	v_mfma_f32_16x16x32_bf16 v[44:47], v[132:135], v[232:235], v[44:47]
	v_mfma_f32_16x16x32_bf16 v[40:43], v[140:143], v[232:235], v[40:43]
	v_mfma_f32_16x16x32_bf16 v[28:31], v[132:135], v[240:243], v[28:31]
	v_mfma_f32_16x16x32_bf16 v[24:27], v[140:143], v[240:243], v[24:27]
	v_mfma_f32_16x16x32_bf16 v[12:15], v[132:135], v[248:251], v[12:15]
	v_mfma_f32_16x16x32_bf16 v[8:11], v[140:143], v[248:251], v[8:11]
	v_mfma_f32_16x16x32_bf16 v[52:55], v[144:147], v[186:189], v[52:55]
	v_mfma_f32_16x16x32_bf16 v[48:51], v[152:155], v[186:189], v[48:51]
	v_mfma_f32_16x16x32_bf16 v[36:39], v[144:147], v[202:205], v[36:39]
	v_mfma_f32_16x16x32_bf16 v[32:35], v[152:155], v[202:205], v[32:35]
	v_mfma_f32_16x16x32_bf16 v[20:23], v[144:147], v[236:239], v[20:23]
	v_mfma_f32_16x16x32_bf16 v[16:19], v[152:155], v[236:239], v[16:19]
	v_mfma_f32_16x16x32_bf16 v[4:7], v[144:147], v[244:247], v[4:7]
	v_mfma_f32_16x16x32_bf16 v[0:3], v[152:155], v[244:247], v[0:3]
	v_mfma_f32_16x16x32_bf16 v[52:55], v[148:151], v[190:193], v[52:55]
	v_mfma_f32_16x16x32_bf16 v[48:51], v[182:185], v[190:193], v[48:51]
	v_mfma_f32_16x16x32_bf16 v[36:39], v[148:151], v[232:235], v[36:39]
	v_mfma_f32_16x16x32_bf16 v[32:35], v[182:185], v[232:235], v[32:35]
	v_mfma_f32_16x16x32_bf16 v[20:23], v[148:151], v[240:243], v[20:23]
	v_mfma_f32_16x16x32_bf16 v[16:19], v[182:185], v[240:243], v[16:19]
	v_mfma_f32_16x16x32_bf16 v[4:7], v[148:151], v[248:251], v[4:7]
	v_mfma_f32_16x16x32_bf16 v[0:3], v[182:185], v[248:251], v[0:3]
	s_setprio 0
	s_barrier
	s_add_i32 s43, s43, 2
	s_addk_i32 s3, 0x100
	s_addk_i32 s42, 0x100
	s_cmp_ge_i32 s43, s101
	s_cbranch_scc0 .LBB0_270
	s_and_b64 vcc, exec, s[20:21]
	s_cbranch_vccz .LBB0_273
	s_barrier
